# GEMM unit scheduler: division by the M-group size (always 8 for 128 row tiles) done with a shift instead of the v_rcp/readfirstlane sequence (26 fewer instructions per unit), on the v78 stack
# speedup vs baseline: 1.0189x; 1.0016x over previous
;     __host__ __device__ bool next(int i, Unit& u) const {
;         const long L = (long)i * G + c; if (L >= nwg) return false;
;         int wgid = (int)L; { const int q = nwg / NXCD, r = nwg % NXCD, xcd = wgid % NXCD, off = wgid / NXCD; wgid = (xcd < r ? xcd * (q + 1) : r * (q + 1) + (xcd - r) * q) + off; }
;         const int nig = WGM * nN, gid = wgid / nig, fm = gid * WGM, gsz = (nM - fm) < WGM ? (nM - fm) : WGM;
;         u.pm = fm + ((wgid % nig) % gsz); u.pn = (wgid % nig) / gsz; return true;
;     }
; template <class Epi, class Sched, bool ALIGN_EPI = false, bool SP2 = false>
; __device__ __forceinline__ void gemm_phase(PG8_LAS unsigned char* lds, const Gemm g, const Sched& S, const Epi& E) {
;     ...
;         const bool has_next = S.next(ui + 1, nxt);
;         const char* nA = has_next ? (const char*)g.A + (size_t)nxt.pm * tstep : cA; const char* nB = has_next ? (const char*)g.Bt + (size_t)nxt.pn * tstep : cB;
.LBB0_296:
	s_add_i32 s63, s63, 1
	s_mul_i32 s8, s63, s43
	s_mul_hi_u32 s9, s63, s42
	s_add_i32 s9, s9, s8
	s_mul_i32 s8, s63, s42
	s_add_u32 s8, s8, s2
	s_addc_u32 s9, s9, s3
	v_cmp_ge_i64_e32 vcc, s[8:9], v[150:151]
	v_cmp_lt_i64_e64 s[10:11], s[8:9], v[150:151]
	s_cbranch_vccnz .LBB0_298
	s_ashr_i32 s9, s8, 31
	s_lshr_b32 s9, s9, 29
	s_add_i32 s9, s8, s9
	s_ashr_i32 s13, s9, 3
	s_and_b32 s9, s9, -8
	s_sub_i32 s8, s8, s9
	s_cmp_lt_i32 s8, 0
	s_cselect_b32 s9, s34, s31
	s_mul_i32 s8, s9, s8
	s_add_i32 s8, s8, s13
	s_abs_i32 s13, s8
	s_mul_hi_u32 s64, s13, s41
	s_mul_i32 s65, s64, s36
	s_ashr_i32 s9, s8, 31
	s_sub_i32 s13, s13, s65
	s_xor_b32 s9, s9, s37
	s_add_i32 s65, s64, 1
	s_sub_i32 s67, s13, s36
	s_cmp_ge_u32 s13, s36
	s_cselect_b32 s64, s65, s64
	s_cselect_b32 s13, s67, s13
	s_add_i32 s65, s64, 1
	s_cmp_ge_u32 s13, s36
	s_cselect_b32 s13, s65, s64
	s_xor_b32 s13, s13, s9
	s_sub_i32 s9, s13, s9
	s_lshl_b32 s13, s9, 3
	s_sub_i32 s64, 0x80, s13
	s_min_i32 s65, s64, 8
	s_mul_i32 s9, s9, s35
	s_sub_i32 s8, s8, s9
	s_ashr_i32 s64, s8, 3
	s_mul_i32 s9, s64, s65
	s_sub_i32 s8, s8, s9
	s_add_i32 s65, s8, s13

; #define LAS __attribute__((address_space(3)))
;     __host__ __device__ bool next(int i, Unit& u) const {
;         const long L = (long)i * G + c; if (L >= nwg) return false;
;         int wgid = (int)L; { const int q = nwg / NXCD, r = nwg % NXCD, xcd = wgid % NXCD, off = wgid / NXCD; wgid = (xcd < r ? xcd * (q + 1) : r * (q + 1) + (xcd - r) * q) + off; }
;         const int nig = WGM * nN, gid = wgid / nig, fm = gid * WGM, gsz = (nM - fm) < WGM ? (nM - fm) : WGM;
;         u.pm = fm + ((wgid % nig) % gsz); u.pn = (wgid % nig) / gsz; return true;
;     }
; template <bool ALIGN = true, class Epi>
; __device__ __forceinline__ void run_gemm(LAS unsigned char* lds, const bf16_t* A, const bf16_t* Bt, int N, int K, const Epi& E) {
;   asm volatile("" : "+s"(N), "+s"(K));
;   pg8::Gemm g{A, Bt, NTOK, N, K};
;   pg8::StaticOrder S; S.init(NTOK, N, (int)gridDim.x, (int)blockIdx.x);
;   pg8::gemm_phase<Epi, pg8::StaticOrder, ALIGN, true>(lds, g, S, E);
.LBB0_355:
	s_or_b64 exec, exec, s[46:47]
	s_mov_b64 s[6:7], s[0:1]
	s_waitcnt lgkmcnt(0)
	s_barrier
	v_mov_b32_e32 v16, v254
	v_mov_b64_e32 v[4:5], s[6:7]
	s_waitcnt vmcnt(0)
	flat_load_dwordx4 v[0:3], v[4:5] offset:192
	flat_load_dwordx2 v[158:159], v[4:5] offset:216
	flat_load_dwordx2 v[160:161], v[4:5] offset:232
	flat_load_dwordx2 v[162:163], v[4:5] offset:328
	s_movk_i32 s7, 0x400
	s_movk_i32 s6, 0xb00
	s_ashr_i32 s8, s7, 31
	s_lshr_b32 s8, s8, 24
	s_add_i32 s7, s7, s8
	s_ashr_i32 s12, s7, 8
	s_lshl_b32 s8, s12, 7
	s_cmp_lt_i32 s2, s8
	s_cselect_b64 s[10:11], -1, 0
	s_cmp_ge_i32 s2, s8
	v_readfirstlane_b32 s9, v16
	s_cbranch_scc1 .LBB0_357
	s_lshl_b32 s15, s12, 3
	s_abs_i32 s16, s15
	v_cvt_f32_u32_e32 v4, s16
	s_lshr_b32 s13, s3, 29
	s_add_i32 s13, s2, s13
	s_ashr_i32 s14, s13, 3
	v_rcp_iflag_f32_e32 v4, v4
	s_and_b32 s13, s13, -8
	s_sub_i32 s13, s2, s13
	s_lshl_b32 s7, s12, 4
	v_mul_f32_e32 v4, 0x4f7ffffe, v4
	v_cvt_u32_f32_e32 v4, v4
	s_lshr_b32 s17, s13, 31
	s_or_b32 s7, s7, s17
	s_sub_i32 s17, 0, s16
	v_readfirstlane_b32 s18, v4
	s_mul_i32 s7, s7, s13
	s_mul_i32 s17, s17, s18
	s_add_i32 s7, s7, s14
	s_mul_hi_u32 s17, s18, s17
	s_abs_i32 s14, s7
	s_add_i32 s18, s18, s17
	s_mul_hi_u32 s17, s14, s18
	s_mul_i32 s18, s17, s16
	s_xor_b32 s13, s7, s15
	s_sub_i32 s14, s14, s18
	s_ashr_i32 s13, s13, 31
	s_add_i32 s18, s17, 1
	s_sub_i32 s19, s14, s16
	s_cmp_ge_u32 s14, s16
	s_cselect_b32 s17, s18, s17
	s_cselect_b32 s14, s19, s14
	s_add_i32 s18, s17, 1
	s_cmp_ge_u32 s14, s16
	s_cselect_b32 s14, s18, s17
	s_xor_b32 s14, s14, s13
	s_sub_i32 s13, s14, s13
	s_lshl_b32 s14, s13, 3
	s_sub_i32 s16, 0x80, s14
	s_min_i32 s16, s16, 8
	s_mul_i32 s13, s13, s15
	s_sub_i32 s7, s7, s13
	s_ashr_i32 s20, s7, 3
	s_mul_i32 s13, s20, s16
	s_sub_i32 s7, s7, s13
	s_add_i32 s28, s7, s14

;     __host__ __device__ bool next(int i, Unit& u) const {
;         const long L = (long)i * G + c; if (L >= nwg) return false;
;         int wgid = (int)L; { const int q = nwg / NXCD, r = nwg % NXCD, xcd = wgid % NXCD, off = wgid / NXCD; wgid = (xcd < r ? xcd * (q + 1) : r * (q + 1) + (xcd - r) * q) + off; }
;         const int nig = WGM * nN, gid = wgid / nig, fm = gid * WGM, gsz = (nM - fm) < WGM ? (nM - fm) : WGM;
;         u.pm = fm + ((wgid % nig) % gsz); u.pn = (wgid % nig) / gsz; return true;
;     }
; template <class Epi, class Sched, bool ALIGN_EPI = false, bool SP2 = false>
; __device__ __forceinline__ void gemm_phase(PG8_LAS unsigned char* lds, const Gemm g, const Sched& S, const Epi& E) {
;     ...
;         const bool has_next = S.next(ui + 1, nxt);
;         const char* nA = has_next ? (const char*)g.A + (size_t)nxt.pm * tstep : cA; const char* nB = has_next ? (const char*)g.Bt + (size_t)nxt.pn * tstep : cB;
.LBB0_363:
	s_add_i32 s60, s60, 1
	s_mul_i32 s10, s60, s43
	s_mul_hi_u32 s11, s60, s42
	s_add_i32 s11, s11, s10
	s_mul_i32 s10, s60, s42
	s_add_u32 s10, s10, s2
	s_addc_u32 s11, s11, s3
	v_cmp_ge_i64_e32 vcc, s[10:11], v[176:177]
	v_cmp_lt_i64_e64 s[12:13], s[10:11], v[176:177]
	s_cbranch_vccnz .LBB0_365
	s_ashr_i32 s11, s10, 31
	s_lshr_b32 s11, s11, 29
	s_add_i32 s11, s10, s11
	s_ashr_i32 s29, s11, 3
	s_and_b32 s11, s11, -8
	s_sub_i32 s10, s10, s11
	s_lshr_b32 s11, s10, 31
	s_or_b32 s11, s11, s51
	s_mul_i32 s10, s11, s10
	s_add_i32 s10, s10, s29
	s_abs_i32 s29, s10
	s_mul_hi_u32 s61, s29, s53
	s_mul_i32 s62, s61, s50
	s_ashr_i32 s11, s10, 31
	s_sub_i32 s29, s29, s62
	s_xor_b32 s11, s11, s52
	s_add_i32 s62, s61, 1
	s_sub_i32 s63, s29, s50
	s_cmp_ge_u32 s29, s50
	s_cselect_b32 s61, s62, s61
	s_cselect_b32 s29, s63, s29
	s_add_i32 s62, s61, 1
	s_cmp_ge_u32 s29, s50
	s_cselect_b32 s29, s62, s61
	s_xor_b32 s29, s29, s11
	s_sub_i32 s11, s29, s11
	s_lshl_b32 s29, s11, 3
	s_sub_i32 s61, 0x80, s29
	s_min_i32 s62, s61, 8
	s_mul_i32 s11, s11, s49
	s_sub_i32 s10, s10, s11
	s_ashr_i32 s61, s10, 3
	s_mul_i32 s11, s61, s62
	s_sub_i32 s10, s10, s11
	s_add_i32 s62, s10, s29

; #define LAS __attribute__((address_space(3)))
;     __host__ __device__ bool next(int i, Unit& u) const {
;         const long L = (long)i * G + c; if (L >= nwg) return false;
;         int wgid = (int)L; { const int q = nwg / NXCD, r = nwg % NXCD, xcd = wgid % NXCD, off = wgid / NXCD; wgid = (xcd < r ? xcd * (q + 1) : r * (q + 1) + (xcd - r) * q) + off; }
;         const int nig = WGM * nN, gid = wgid / nig, fm = gid * WGM, gsz = (nM - fm) < WGM ? (nM - fm) : WGM;
;         u.pm = fm + ((wgid % nig) % gsz); u.pn = (wgid % nig) / gsz; return true;
;     }
; template <bool ALIGN = true, class Epi>
; __device__ __forceinline__ void run_gemm(LAS unsigned char* lds, const bf16_t* A, const bf16_t* Bt, int N, int K, const Epi& E) {
;   asm volatile("" : "+s"(N), "+s"(K));
;   pg8::Gemm g{A, Bt, NTOK, N, K};
;   pg8::StaticOrder S; S.init(NTOK, N, (int)gridDim.x, (int)blockIdx.x);
;   pg8::gemm_phase<Epi, pg8::StaticOrder, ALIGN, true>(lds, g, S, E);
.LBB0_438:
	s_or_b64 exec, exec, s[46:47]
	s_load_dwordx2 s[98:99], s[0:1], 0xe8
	s_mov_b64 s[6:7], s[0:1]
	s_waitcnt lgkmcnt(0)
	s_barrier
	v_mov_b32_e32 v12, v254
	s_waitcnt vmcnt(0)
	v_mov_b64_e32 v[0:1], s[6:7]
	flat_load_dwordx2 v[140:141], v[0:1] offset:192
	flat_load_dwordx2 v[142:143], v[0:1] offset:392
	s_movk_i32 s7, 0x600
	s_movk_i32 s6, 0x400
	s_ashr_i32 s8, s7, 31
	s_lshr_b32 s8, s8, 24
	s_add_i32 s7, s7, s8
	s_ashr_i32 s12, s7, 8
	s_lshl_b32 s10, s12, 7
	s_cmp_lt_i32 s2, s10
	s_cselect_b64 s[8:9], -1, 0
	s_cmp_ge_i32 s2, s10
	v_readfirstlane_b32 s11, v12
	s_cbranch_scc1 .LBB0_440
	s_lshl_b32 s15, s12, 3
	s_abs_i32 s16, s15
	v_cvt_f32_u32_e32 v0, s16
	s_lshr_b32 s13, s3, 29
	s_add_i32 s13, s2, s13
	s_ashr_i32 s14, s13, 3
	v_rcp_iflag_f32_e32 v0, v0
	s_and_b32 s13, s13, -8
	s_sub_i32 s13, s2, s13
	s_lshl_b32 s7, s12, 4
	v_mul_f32_e32 v0, 0x4f7ffffe, v0
	v_cvt_u32_f32_e32 v0, v0
	s_lshr_b32 s17, s13, 31
	s_or_b32 s7, s7, s17
	s_sub_i32 s17, 0, s16
	v_readfirstlane_b32 s18, v0
	s_mul_i32 s7, s7, s13
	s_mul_i32 s17, s17, s18
	s_add_i32 s7, s7, s14
	s_mul_hi_u32 s17, s18, s17
	s_abs_i32 s14, s7
	s_add_i32 s18, s18, s17
	s_mul_hi_u32 s17, s14, s18
	s_mul_i32 s18, s17, s16
	s_xor_b32 s13, s7, s15
	s_sub_i32 s14, s14, s18
	s_ashr_i32 s13, s13, 31
	s_add_i32 s18, s17, 1
	s_sub_i32 s19, s14, s16
	s_cmp_ge_u32 s14, s16
	s_cselect_b32 s17, s18, s17
	s_cselect_b32 s14, s19, s14
	s_add_i32 s18, s17, 1
	s_cmp_ge_u32 s14, s16
	s_cselect_b32 s14, s18, s17
	s_xor_b32 s14, s14, s13
	s_sub_i32 s13, s14, s13
	s_lshl_b32 s14, s13, 3
	s_sub_i32 s16, 0x80, s14
	s_min_i32 s16, s16, 8
	s_mul_i32 s13, s13, s15
	s_sub_i32 s7, s7, s13
	s_ashr_i32 s75, s7, 3
	s_mul_i32 s13, s75, s16
	s_sub_i32 s7, s7, s13
	s_add_i32 s14, s7, s14

;     __host__ __device__ bool next(int i, Unit& u) const {
;         const long L = (long)i * G + c; if (L >= nwg) return false;
;         int wgid = (int)L; { const int q = nwg / NXCD, r = nwg % NXCD, xcd = wgid % NXCD, off = wgid / NXCD; wgid = (xcd < r ? xcd * (q + 1) : r * (q + 1) + (xcd - r) * q) + off; }
;         const int nig = WGM * nN, gid = wgid / nig, fm = gid * WGM, gsz = (nM - fm) < WGM ? (nM - fm) : WGM;
;         u.pm = fm + ((wgid % nig) % gsz); u.pn = (wgid % nig) / gsz; return true;
;     }
; template <class Epi, class Sched, bool ALIGN_EPI = false, bool SP2 = false>
; __device__ __forceinline__ void gemm_phase(PG8_LAS unsigned char* lds, const Gemm g, const Sched& S, const Epi& E) {
;     ...
;         const bool has_next = S.next(ui + 1, nxt);
;         const char* nA = has_next ? (const char*)g.A + (size_t)nxt.pm * tstep : cA; const char* nB = has_next ? (const char*)g.Bt + (size_t)nxt.pn * tstep : cB;
.LBB0_446:
	s_add_i32 s72, s72, 1
	s_mul_i32 s10, s72, s43
	s_mul_hi_u32 s11, s72, s42
	s_add_i32 s11, s11, s10
	s_mul_i32 s10, s72, s42
	s_add_u32 s10, s10, s2
	s_addc_u32 s11, s11, s3
	v_cmp_ge_i64_e32 vcc, s[10:11], v[162:163]
	v_cmp_lt_i64_e64 s[12:13], s[10:11], v[162:163]
	s_cbranch_vccnz .LBB0_448
	s_ashr_i32 s11, s10, 31
	s_lshr_b32 s11, s11, 29
	s_add_i32 s11, s10, s11
	s_ashr_i32 s15, s11, 3
	s_and_b32 s11, s11, -8
	s_sub_i32 s10, s10, s11
	s_lshr_b32 s11, s10, 31
	s_or_b32 s11, s11, s66
	s_mul_i32 s10, s11, s10
	s_add_i32 s10, s10, s15
	s_abs_i32 s15, s10
	s_mul_hi_u32 s46, s15, s68
	s_mul_i32 s47, s46, s65
	s_ashr_i32 s11, s10, 31
	s_sub_i32 s15, s15, s47
	s_xor_b32 s11, s11, s67
	s_add_i32 s47, s46, 1
	s_sub_i32 s48, s15, s65
	s_cmp_ge_u32 s15, s65
	s_cselect_b32 s46, s47, s46
	s_cselect_b32 s15, s48, s15
	s_add_i32 s47, s46, 1
	s_cmp_ge_u32 s15, s65
	s_cselect_b32 s15, s47, s46
	s_xor_b32 s15, s15, s11
	s_sub_i32 s11, s15, s11
	s_lshl_b32 s15, s11, 3
	s_sub_i32 s46, 0x80, s15
	s_min_i32 s46, s46, 8
	s_mul_i32 s11, s11, s64
	s_sub_i32 s10, s10, s11
	s_ashr_i32 s73, s10, 3
	s_mul_i32 s11, s73, s46
	s_sub_i32 s10, s10, s11
	s_add_i32 s74, s10, s15

; #define LAS __attribute__((address_space(3)))
;     __host__ __device__ bool next(int i, Unit& u) const {
;         const long L = (long)i * G + c; if (L >= nwg) return false;
;         int wgid = (int)L; { const int q = nwg / NXCD, r = nwg % NXCD, xcd = wgid % NXCD, off = wgid / NXCD; wgid = (xcd < r ? xcd * (q + 1) : r * (q + 1) + (xcd - r) * q) + off; }
;         const int nig = WGM * nN, gid = wgid / nig, fm = gid * WGM, gsz = (nM - fm) < WGM ? (nM - fm) : WGM;
;         u.pm = fm + ((wgid % nig) % gsz); u.pn = (wgid % nig) / gsz; return true;
;     }
; template <bool ALIGN = true, class Epi>
; __device__ __forceinline__ void run_gemm(LAS unsigned char* lds, const bf16_t* A, const bf16_t* Bt, int N, int K, const Epi& E) {
;   asm volatile("" : "+s"(N), "+s"(K));
;   pg8::Gemm g{A, Bt, NTOK, N, K};
;   pg8::StaticOrder S; S.init(NTOK, N, (int)gridDim.x, (int)blockIdx.x);
;   pg8::gemm_phase<Epi, pg8::StaticOrder, ALIGN, true>(lds, g, S, E);
.LBB0_619:
	s_or_b64 exec, exec, s[46:47]
	s_mov_b64 s[16:17], s[0:1]
	s_waitcnt lgkmcnt(0)
	s_barrier
	s_movk_i32 s7, 0x300
	v_mov_b64_e32 v[2:3], s[16:17]
	flat_load_dwordx2 v[158:159], v[2:3] offset:504
	flat_load_dwordx2 v[160:161], v[2:3] offset:248
	flat_load_dwordx2 v[0:1], v[2:3] offset:280
	flat_load_dwordx2 v[162:163], v[2:3] offset:448
	flat_load_dwordx2 v[164:165], v[2:3] offset:400
	s_movk_i32 s6, 0x100
	s_ashr_i32 s8, s7, 31
	s_lshr_b32 s8, s8, 24
	s_add_i32 s7, s7, s8
	s_ashr_i32 s14, s7, 8
	s_lshl_b32 s8, s14, 7
	v_mov_b32_e32 v14, v254
	s_cmp_lt_i32 s2, s8
	s_cselect_b64 s[10:11], -1, 0
	s_cmp_ge_i32 s2, s8
	v_readfirstlane_b32 s9, v14
	s_cbranch_scc1 .LBB0_621
	s_lshl_b32 s15, s14, 3
	s_abs_i32 s18, s15
	v_cvt_f32_u32_e32 v2, s18
	s_lshr_b32 s12, s3, 29
	s_add_i32 s12, s2, s12
	s_ashr_i32 s13, s12, 3
	v_rcp_iflag_f32_e32 v2, v2
	s_and_b32 s12, s12, -8
	s_sub_i32 s12, s2, s12
	s_lshl_b32 s7, s14, 4
	v_mul_f32_e32 v2, 0x4f7ffffe, v2
	v_cvt_u32_f32_e32 v2, v2
	s_lshr_b32 s19, s12, 31
	s_or_b32 s7, s7, s19
	s_sub_i32 s19, 0, s18
	v_readfirstlane_b32 s20, v2
	s_mul_i32 s7, s7, s12
	s_mul_i32 s19, s19, s20
	s_add_i32 s7, s7, s13
	s_mul_hi_u32 s19, s20, s19
	s_abs_i32 s13, s7
	s_add_i32 s20, s20, s19
	s_mul_hi_u32 s19, s13, s20
	s_mul_i32 s20, s19, s18
	s_xor_b32 s12, s7, s15
	s_sub_i32 s13, s13, s20
	s_ashr_i32 s12, s12, 31
	s_add_i32 s20, s19, 1
	s_sub_i32 s21, s13, s18
	s_cmp_ge_u32 s13, s18
	s_cselect_b32 s19, s20, s19
	s_cselect_b32 s13, s21, s13
	s_add_i32 s20, s19, 1
	s_cmp_ge_u32 s13, s18
	s_cselect_b32 s13, s20, s19
	s_xor_b32 s13, s13, s12
	s_sub_i32 s12, s13, s12
	s_lshl_b32 s13, s12, 3
	s_sub_i32 s18, 0x80, s13
	s_min_i32 s18, s18, 8
	s_mul_i32 s12, s12, s15
	s_sub_i32 s7, s7, s12
	s_ashr_i32 s12, s7, 3
	s_mul_i32 s15, s12, s18
	s_sub_i32 s7, s7, s15
	s_add_i32 s13, s7, s13

;     __host__ __device__ bool next(int i, Unit& u) const {
;         const long L = (long)i * G + c; if (L >= nwg) return false;
;         int wgid = (int)L; { const int q = nwg / NXCD, r = nwg % NXCD, xcd = wgid % NXCD, off = wgid / NXCD; wgid = (xcd < r ? xcd * (q + 1) : r * (q + 1) + (xcd - r) * q) + off; }
;         const int nig = WGM * nN, gid = wgid / nig, fm = gid * WGM, gsz = (nM - fm) < WGM ? (nM - fm) : WGM;
;         u.pm = fm + ((wgid % nig) % gsz); u.pn = (wgid % nig) / gsz; return true;
;     }
; template <class Epi, class Sched, bool ALIGN_EPI = false, bool SP2 = false>
; __device__ __forceinline__ void gemm_phase(PG8_LAS unsigned char* lds, const Gemm g, const Sched& S, const Epi& E) {
;     ...
;         const bool has_next = S.next(ui + 1, nxt);
;         const char* nA = has_next ? (const char*)g.A + (size_t)nxt.pm * tstep : cA; const char* nB = has_next ? (const char*)g.Bt + (size_t)nxt.pn * tstep : cB;
.LBB0_627:
	s_add_i32 s53, s53, 1
	s_mul_i32 s8, s53, s43
	s_mul_hi_u32 s9, s53, s42
	s_add_i32 s9, s9, s8
	s_mul_i32 s8, s53, s42
	s_add_u32 s8, s8, s2
	s_addc_u32 s9, s9, s3
	v_cmp_ge_i64_e32 vcc, s[8:9], v[182:183]
	v_cmp_lt_i64_e64 s[10:11], s[8:9], v[182:183]
	s_cbranch_vccnz .LBB0_629
	s_ashr_i32 s9, s8, 31
	s_lshr_b32 s9, s9, 29
	s_add_i32 s9, s8, s9
	s_ashr_i32 s14, s9, 3
	s_and_b32 s9, s9, -8
	s_sub_i32 s8, s8, s9
	s_lshr_b32 s9, s8, 31
	s_or_b32 s9, s9, s61
	s_mul_i32 s8, s9, s8
	s_add_i32 s8, s8, s14
	s_abs_i32 s14, s8
	s_mul_hi_u32 s15, s14, s63
	s_mul_i32 s36, s15, s60
	s_ashr_i32 s9, s8, 31
	s_sub_i32 s14, s14, s36
	s_xor_b32 s9, s9, s62
	s_add_i32 s36, s15, 1
	s_sub_i32 s37, s14, s60
	s_cmp_ge_u32 s14, s60
	s_cselect_b32 s15, s36, s15
	s_cselect_b32 s14, s37, s14
	s_add_i32 s36, s15, 1
	s_cmp_ge_u32 s14, s60
	s_cselect_b32 s14, s36, s15
	s_xor_b32 s14, s14, s9
	s_sub_i32 s9, s14, s9
	s_lshl_b32 s14, s9, 3
	s_sub_i32 s15, 0x80, s14
	s_min_i32 s15, s15, 8
	s_mul_i32 s9, s9, s59
	s_sub_i32 s8, s8, s9
	s_ashr_i32 s68, s8, 3
	s_mul_i32 s9, s68, s15
	s_sub_i32 s8, s8, s9
	s_add_i32 s69, s8, s14

;     __host__ __device__ bool next(int i, Unit& u) const {
;         const long L = (long)i * G + c; if (L >= nwg) return false;
;         int wgid = (int)L; { const int q = nwg / NXCD, r = nwg % NXCD, xcd = wgid % NXCD, off = wgid / NXCD; wgid = (xcd < r ? xcd * (q + 1) : r * (q + 1) + (xcd - r) * q) + off; }
;         const int nig = WGM * nN, gid = wgid / nig, fm = gid * WGM, gsz = (nM - fm) < WGM ? (nM - fm) : WGM;
;         u.pm = fm + ((wgid % nig) % gsz); u.pn = (wgid % nig) / gsz; return true;
;     }
; template <class Epi, class Sched, bool ALIGN_EPI = false, bool SP2 = false>
; __device__ __forceinline__ void gemm_phase(PG8_LAS unsigned char* lds, const Gemm g, const Sched& S, const Epi& E) {
;     ...
;         const bool has_next = S.next(ui + 1, nxt);
;         const char* nA = has_next ? (const char*)g.A + (size_t)nxt.pm * tstep : cA; const char* nB = has_next ? (const char*)g.Bt + (size_t)nxt.pn * tstep : cB;
.LBB0_714:
	s_add_i32 s47, s47, 1
	s_mul_i32 s6, s47, s43
	s_mul_hi_u32 s7, s47, s42
	s_add_i32 s7, s7, s6
	s_mul_i32 s6, s47, s42
	s_add_u32 s6, s6, s2
	s_addc_u32 s7, s7, s3
	v_cmp_ge_i64_e32 vcc, s[6:7], v[180:181]
	v_cmp_lt_i64_e64 s[8:9], s[6:7], v[180:181]
	s_cbranch_vccnz .LBB0_716
	s_ashr_i32 s7, s6, 31
	s_lshr_b32 s7, s7, 29
	s_add_i32 s7, s6, s7
	s_ashr_i32 s10, s7, 3
	s_and_b32 s7, s7, -8
	s_sub_i32 s6, s6, s7
	s_lshr_b32 s7, s6, 31
	s_or_b32 s7, s7, s56
	s_mul_i32 s6, s7, s6
	s_add_i32 s6, s6, s10
	s_abs_i32 s10, s6
	s_mul_hi_u32 s11, s10, s58
	s_mul_i32 s31, s11, s55
	s_ashr_i32 s7, s6, 31
	s_sub_i32 s10, s10, s31
	s_xor_b32 s7, s7, s57
	s_add_i32 s31, s11, 1
	s_sub_i32 s66, s10, s55
	s_cmp_ge_u32 s10, s55
	s_cselect_b32 s11, s31, s11
	s_cselect_b32 s10, s66, s10
	s_add_i32 s31, s11, 1
	s_cmp_ge_u32 s10, s55
	s_cselect_b32 s10, s31, s11
	s_xor_b32 s10, s10, s7
	s_sub_i32 s7, s10, s7
	s_lshl_b32 s10, s7, 3
	s_sub_i32 s11, 0x80, s10
	s_min_i32 s11, s11, 8
	s_mul_i32 s7, s7, s54
	s_sub_i32 s6, s6, s7
	s_ashr_i32 s66, s6, 3
	s_mul_i32 s7, s66, s11
	s_sub_i32 s6, s6, s7
	s_add_i32 s67, s6, s10

; #define LAS __attribute__((address_space(3)))
;     __host__ __device__ bool next(int i, Unit& u) const {
;         const long L = (long)i * G + c; if (L >= nwg) return false;
;         int wgid = (int)L; { const int q = nwg / NXCD, r = nwg % NXCD, xcd = wgid % NXCD, off = wgid / NXCD; wgid = (xcd < r ? xcd * (q + 1) : r * (q + 1) + (xcd - r) * q) + off; }
;         const int nig = WGM * nN, gid = wgid / nig, fm = gid * WGM, gsz = (nM - fm) < WGM ? (nM - fm) : WGM;
;         u.pm = fm + ((wgid % nig) % gsz); u.pn = (wgid % nig) / gsz; return true;
;     }
; template <bool ALIGN = true, class Epi>
; __device__ __forceinline__ void run_gemm(LAS unsigned char* lds, const bf16_t* A, const bf16_t* Bt, int N, int K, const Epi& E) {
;   asm volatile("" : "+s"(N), "+s"(K));
;   pg8::Gemm g{A, Bt, NTOK, N, K};
;   pg8::StaticOrder S; S.init(NTOK, N, (int)gridDim.x, (int)blockIdx.x);
;   pg8::gemm_phase<Epi, pg8::StaticOrder, ALIGN, true>(lds, g, S, E);
.LBB0_924:
	s_or_b64 exec, exec, s[46:47]
	s_mov_b64 s[6:7], s[0:1]
	s_waitcnt lgkmcnt(0)
	s_barrier
	v_mov_b32_e32 v12, v254
	s_waitcnt vmcnt(0)
	v_mov_b64_e32 v[0:1], s[6:7]
	flat_load_dwordx2 v[152:153], v[0:1] offset:192
	flat_load_dwordx2 v[154:155], v[0:1] offset:232
	flat_load_dwordx2 v[158:159], v[0:1] offset:496
	flat_load_dwordx2 v[160:161], v[0:1] offset:416
	s_movk_i32 s7, 0x400
	s_movk_i32 s6, 0x400
	s_ashr_i32 s8, s7, 31
	s_lshr_b32 s8, s8, 24
	s_add_i32 s7, s7, s8
	s_ashr_i32 s12, s7, 8
	s_lshl_b32 s8, s12, 7
	s_cmp_lt_i32 s2, s8
	s_cselect_b64 s[10:11], -1, 0
	s_cmp_ge_i32 s2, s8
	v_readfirstlane_b32 s9, v12
	s_cbranch_scc1 .LBB0_926
	s_lshl_b32 s15, s12, 3
	s_abs_i32 s16, s15
	v_cvt_f32_u32_e32 v0, s16
	s_lshr_b32 s13, s3, 29
	s_add_i32 s13, s2, s13
	s_ashr_i32 s14, s13, 3
	v_rcp_iflag_f32_e32 v0, v0
	s_and_b32 s13, s13, -8
	s_sub_i32 s13, s2, s13
	s_lshl_b32 s7, s12, 4
	v_mul_f32_e32 v0, 0x4f7ffffe, v0
	v_cvt_u32_f32_e32 v0, v0
	s_lshr_b32 s17, s13, 31
	s_or_b32 s7, s7, s17
	s_sub_i32 s17, 0, s16
	v_readfirstlane_b32 s18, v0
	s_mul_i32 s7, s7, s13
	s_mul_i32 s17, s17, s18
	s_add_i32 s7, s7, s14
	s_mul_hi_u32 s17, s18, s17
	s_abs_i32 s14, s7
	s_add_i32 s18, s18, s17
	s_mul_hi_u32 s17, s14, s18
	s_mul_i32 s18, s17, s16
	s_xor_b32 s13, s7, s15
	s_sub_i32 s14, s14, s18
	s_ashr_i32 s13, s13, 31
	s_add_i32 s18, s17, 1
	s_sub_i32 s19, s14, s16
	s_cmp_ge_u32 s14, s16
	s_cselect_b32 s17, s18, s17
	s_cselect_b32 s14, s19, s14
	s_add_i32 s18, s17, 1
	s_cmp_ge_u32 s14, s16
	s_cselect_b32 s14, s18, s17
	s_xor_b32 s14, s14, s13
	s_sub_i32 s13, s14, s13
	s_lshl_b32 s14, s13, 3
	s_sub_i32 s16, 0x80, s14
	s_min_i32 s16, s16, 8
	s_mul_i32 s13, s13, s15
	s_sub_i32 s7, s7, s13
	s_ashr_i32 s20, s7, 3
	s_mul_i32 s13, s20, s16
	s_sub_i32 s7, s7, s13
	s_add_i32 s28, s7, s14

;     __host__ __device__ bool next(int i, Unit& u) const {
;         const long L = (long)i * G + c; if (L >= nwg) return false;
;         int wgid = (int)L; { const int q = nwg / NXCD, r = nwg % NXCD, xcd = wgid % NXCD, off = wgid / NXCD; wgid = (xcd < r ? xcd * (q + 1) : r * (q + 1) + (xcd - r) * q) + off; }
;         const int nig = WGM * nN, gid = wgid / nig, fm = gid * WGM, gsz = (nM - fm) < WGM ? (nM - fm) : WGM;
;         u.pm = fm + ((wgid % nig) % gsz); u.pn = (wgid % nig) / gsz; return true;
;     }
; template <class Epi, class Sched, bool ALIGN_EPI = false, bool SP2 = false>
; __device__ __forceinline__ void gemm_phase(PG8_LAS unsigned char* lds, const Gemm g, const Sched& S, const Epi& E) {
;     ...
;         const bool has_next = S.next(ui + 1, nxt);
;         const char* nA = has_next ? (const char*)g.A + (size_t)nxt.pm * tstep : cA; const char* nB = has_next ? (const char*)g.Bt + (size_t)nxt.pn * tstep : cB;
.LBB0_932:
	s_add_i32 s60, s60, 1
	s_mul_i32 s10, s60, s43
	s_mul_hi_u32 s11, s60, s42
	s_add_i32 s11, s11, s10
	s_mul_i32 s10, s60, s42
	s_add_u32 s10, s10, s2
	s_addc_u32 s11, s11, s3
	v_cmp_ge_i64_e32 vcc, s[10:11], v[174:175]
	v_cmp_lt_i64_e64 s[12:13], s[10:11], v[174:175]
	s_cbranch_vccnz .LBB0_934
	s_ashr_i32 s11, s10, 31
	s_lshr_b32 s11, s11, 29
	s_add_i32 s11, s10, s11
	s_ashr_i32 s29, s11, 3
	s_and_b32 s11, s11, -8
	s_sub_i32 s10, s10, s11
	s_lshr_b32 s11, s10, 31
	s_or_b32 s11, s11, s51
	s_mul_i32 s10, s11, s10
	s_add_i32 s10, s10, s29
	s_abs_i32 s29, s10
	s_mul_hi_u32 s61, s29, s54
	s_mul_i32 s62, s61, s50
	s_ashr_i32 s11, s10, 31
	s_sub_i32 s29, s29, s62
	s_xor_b32 s11, s11, s52
	s_add_i32 s62, s61, 1
	s_sub_i32 s63, s29, s50
	s_cmp_ge_u32 s29, s50
	s_cselect_b32 s61, s62, s61
	s_cselect_b32 s29, s63, s29
	s_add_i32 s62, s61, 1
	s_cmp_ge_u32 s29, s50
	s_cselect_b32 s29, s62, s61
	s_xor_b32 s29, s29, s11
	s_sub_i32 s11, s29, s11
	s_lshl_b32 s29, s11, 3
	s_sub_i32 s61, 0x80, s29
	s_min_i32 s62, s61, 8
	s_mul_i32 s11, s11, s49
	s_sub_i32 s10, s10, s11
	s_ashr_i32 s61, s10, 3
	s_mul_i32 s11, s61, s62
	s_sub_i32 s10, s10, s11
	s_add_i32 s62, s10, s29

;     __host__ __device__ bool next(int i, Unit& u) const {
;         const long L = (long)i * G + c; if (L >= nwg) return false;
;         int wgid = (int)L; { const int q = nwg / NXCD, r = nwg % NXCD, xcd = wgid % NXCD, off = wgid / NXCD; wgid = (xcd < r ? xcd * (q + 1) : r * (q + 1) + (xcd - r) * q) + off; }
;         const int nig = WGM * nN, gid = wgid / nig, fm = gid * WGM, gsz = (nM - fm) < WGM ? (nM - fm) : WGM;
;         u.pm = fm + ((wgid % nig) % gsz); u.pn = (wgid % nig) / gsz; return true;
;     }
; template <class Epi, class Sched, bool ALIGN_EPI = false, bool SP2 = false>
; __device__ __forceinline__ void gemm_phase(PG8_LAS unsigned char* lds, const Gemm g, const Sched& S, const Epi& E) {
;     ...
;         const bool has_next = S.next(ui + 1, nxt);
;         const char* nA = has_next ? (const char*)g.A + (size_t)nxt.pm * tstep : cA; const char* nB = has_next ? (const char*)g.Bt + (size_t)nxt.pn * tstep : cB;
.LBB0_1013:
	s_add_i32 s64, s64, 1
	s_mul_i32 s8, s64, s43
	s_mul_hi_u32 s9, s64, s42
	s_add_i32 s9, s9, s8
	s_mul_i32 s8, s64, s42
	s_add_u32 s8, s8, s2
	s_addc_u32 s9, s9, s3
	v_cmp_ge_i64_e32 vcc, s[8:9], v[150:151]
	v_cmp_lt_i64_e64 s[10:11], s[8:9], v[150:151]
	s_cbranch_vccnz .LBB0_1015
	s_ashr_i32 s9, s8, 31
	s_lshr_b32 s9, s9, 29
	s_add_i32 s9, s8, s9
	s_ashr_i32 s13, s9, 3
	s_and_b32 s9, s9, -8
	s_sub_i32 s8, s8, s9
	s_cmp_lt_i32 s8, 0
	s_cselect_b32 s9, s34, s31
	s_mul_i32 s8, s9, s8
	s_add_i32 s8, s8, s13
	s_abs_i32 s13, s8
	s_mul_hi_u32 s65, s13, s41
	s_mul_i32 s66, s65, s36
	s_ashr_i32 s9, s8, 31
	s_sub_i32 s13, s13, s66
	s_xor_b32 s9, s9, s37
	s_add_i32 s66, s65, 1
	s_sub_i32 s68, s13, s36
	s_cmp_ge_u32 s13, s36
	s_cselect_b32 s65, s66, s65
	s_cselect_b32 s13, s68, s13
	s_add_i32 s66, s65, 1
	s_cmp_ge_u32 s13, s36
	s_cselect_b32 s13, s66, s65
	s_xor_b32 s13, s13, s9
	s_sub_i32 s9, s13, s9
	s_lshl_b32 s13, s9, 3
	s_sub_i32 s65, 0x80, s13
	s_min_i32 s66, s65, 8
	s_mul_i32 s9, s9, s35
	s_sub_i32 s8, s8, s9
	s_ashr_i32 s65, s8, 3
	s_mul_i32 s9, s65, s66
	s_sub_i32 s8, s8, s9
	s_add_i32 s66, s8, s13

; #define LAS __attribute__((address_space(3)))
;     __host__ __device__ bool next(int i, Unit& u) const {
;         const long L = (long)i * G + c; if (L >= nwg) return false;
;         int wgid = (int)L; { const int q = nwg / NXCD, r = nwg % NXCD, xcd = wgid % NXCD, off = wgid / NXCD; wgid = (xcd < r ? xcd * (q + 1) : r * (q + 1) + (xcd - r) * q) + off; }
;         const int nig = WGM * nN, gid = wgid / nig, fm = gid * WGM, gsz = (nM - fm) < WGM ? (nM - fm) : WGM;
;         u.pm = fm + ((wgid % nig) % gsz); u.pn = (wgid % nig) / gsz; return true;
; template <bool ALIGN = true, class Epi>
; __device__ __forceinline__ void run_gemm(LAS unsigned char* lds, const bf16_t* A, const bf16_t* Bt, int N, int K, const Epi& E) {
;   asm volatile("" : "+s"(N), "+s"(K));
;   pg8::Gemm g{A, Bt, NTOK, N, K};
;   pg8::StaticOrder S; S.init(NTOK, N, (int)gridDim.x, (int)blockIdx.x);
.LBB0_1072:
	s_or_b64 exec, exec, s[46:47]
	s_mov_b64 s[6:7], s[0:1]
	s_waitcnt lgkmcnt(0)
	s_barrier
	v_mov_b32_e32 v12, v254
	s_waitcnt vmcnt(0)
	v_mov_b64_e32 v[0:1], s[6:7]
	flat_load_dwordx2 v[152:153], v[0:1] offset:192
	flat_load_dwordx2 v[154:155], v[0:1] offset:232
	flat_load_dwordx2 v[158:159], v[0:1] offset:344
	flat_load_dwordx2 v[160:161], v[0:1] offset:216
	s_movk_i32 s7, 0x400
	s_movk_i32 s6, 0xb00
	s_ashr_i32 s8, s7, 31
	s_lshr_b32 s8, s8, 24
	s_add_i32 s7, s7, s8
	s_ashr_i32 s12, s7, 8
	s_lshl_b32 s8, s12, 7
	s_cmp_lt_i32 s2, s8
	s_cselect_b64 s[10:11], -1, 0
	s_cmp_ge_i32 s2, s8
	v_readfirstlane_b32 s9, v12
	s_cbranch_scc1 .LBB0_1074
	s_lshl_b32 s15, s12, 3
	s_abs_i32 s16, s15
	v_cvt_f32_u32_e32 v0, s16
	s_lshr_b32 s13, s3, 29
	s_add_i32 s13, s2, s13
	s_ashr_i32 s14, s13, 3
	v_rcp_iflag_f32_e32 v0, v0
	s_and_b32 s13, s13, -8
	s_sub_i32 s13, s2, s13
	s_lshl_b32 s7, s12, 4
	v_mul_f32_e32 v0, 0x4f7ffffe, v0
	v_cvt_u32_f32_e32 v0, v0
	s_lshr_b32 s17, s13, 31
	s_or_b32 s7, s7, s17
	s_sub_i32 s17, 0, s16
	v_readfirstlane_b32 s18, v0
	s_mul_i32 s7, s7, s13
	s_mul_i32 s17, s17, s18
	s_add_i32 s7, s7, s14
	s_mul_hi_u32 s17, s18, s17
	s_abs_i32 s14, s7
	s_add_i32 s18, s18, s17
	s_mul_hi_u32 s17, s14, s18
	s_mul_i32 s18, s17, s16
	s_xor_b32 s13, s7, s15
	s_sub_i32 s14, s14, s18
	s_ashr_i32 s13, s13, 31
	s_add_i32 s18, s17, 1
	s_sub_i32 s19, s14, s16
	s_cmp_ge_u32 s14, s16
	s_cselect_b32 s17, s18, s17
	s_cselect_b32 s14, s19, s14
	s_add_i32 s18, s17, 1
	s_cmp_ge_u32 s14, s16
	s_cselect_b32 s14, s18, s17
	s_xor_b32 s14, s14, s13
	s_sub_i32 s13, s14, s13
	s_lshl_b32 s14, s13, 3
	s_sub_i32 s16, 0x80, s14
	s_min_i32 s16, s16, 8
	s_mul_i32 s13, s13, s15
	s_sub_i32 s7, s7, s13
	s_ashr_i32 s20, s7, 3
	s_mul_i32 s13, s20, s16
	s_sub_i32 s7, s7, s13
	s_add_i32 s28, s7, s14

;     __host__ __device__ bool next(int i, Unit& u) const {
;         const long L = (long)i * G + c; if (L >= nwg) return false;
;         int wgid = (int)L; { const int q = nwg / NXCD, r = nwg % NXCD, xcd = wgid % NXCD, off = wgid / NXCD; wgid = (xcd < r ? xcd * (q + 1) : r * (q + 1) + (xcd - r) * q) + off; }
;         const int nig = WGM * nN, gid = wgid / nig, fm = gid * WGM, gsz = (nM - fm) < WGM ? (nM - fm) : WGM;
;         u.pm = fm + ((wgid % nig) % gsz); u.pn = (wgid % nig) / gsz; return true;
; template <class Epi, class Sched, bool ALIGN_EPI = false, bool SP2 = false>
; __device__ __forceinline__ void gemm_phase(PG8_LAS unsigned char* lds, const Gemm g, const Sched& S, const Epi& E) {
;     ...
;         const bool has_next = S.next(ui + 1, nxt);
;         const char* nA = has_next ? (const char*)g.A + (size_t)nxt.pm * tstep : cA; const char* nB = has_next ? (const char*)g.Bt + (size_t)nxt.pn * tstep : cB;
.LBB0_1161:
	s_add_i32 s66, s66, 1
	s_mul_i32 s8, s66, s43
	s_mul_hi_u32 s9, s66, s42
	s_add_i32 s9, s9, s8
	s_mul_i32 s8, s66, s42
	s_add_u32 s8, s8, s2
	s_addc_u32 s9, s9, s3
	v_cmp_ge_i64_e32 vcc, s[8:9], v[148:149]
	v_cmp_lt_i64_e64 s[10:11], s[8:9], v[148:149]
	s_cbranch_vccnz .LBB0_1163
	s_ashr_i32 s9, s8, 31
	s_lshr_b32 s9, s9, 29
	s_add_i32 s9, s8, s9
	s_ashr_i32 s67, s9, 3
	s_and_b32 s9, s9, -8
	s_sub_i32 s8, s8, s9
	s_cmp_lt_i32 s8, 0
	s_cselect_b32 s9, s30, s23
	s_mul_i32 s8, s9, s8
	s_add_i32 s8, s8, s67
	s_abs_i32 s67, s8
	s_mul_hi_u32 s68, s67, s36
	s_mul_i32 s71, s68, s34
	s_ashr_i32 s9, s8, 31
	s_sub_i32 s67, s67, s71
	s_xor_b32 s9, s9, s35
	s_add_i32 s71, s68, 1
	s_sub_i32 s72, s67, s34
	s_cmp_ge_u32 s67, s34
	s_cselect_b32 s68, s71, s68
	s_cselect_b32 s67, s72, s67
	s_add_i32 s71, s68, 1
	s_cmp_ge_u32 s67, s34
	s_cselect_b32 s67, s71, s68
	s_xor_b32 s67, s67, s9
	s_sub_i32 s9, s67, s9
	s_lshl_b32 s68, s9, 3
	s_sub_i32 s67, 0x80, s68
	s_min_i32 s71, s67, 8
	s_mul_i32 s9, s9, s31
	s_sub_i32 s8, s8, s9
	s_ashr_i32 s67, s8, 3
	s_mul_i32 s9, s67, s71
	s_sub_i32 s8, s8, s9
	s_add_i32 s68, s8, s68

; #define LAS __attribute__((address_space(3)))
;     __host__ __device__ bool next(int i, Unit& u) const {
;         const long L = (long)i * G + c; if (L >= nwg) return false;
;         int wgid = (int)L; { const int q = nwg / NXCD, r = nwg % NXCD, xcd = wgid % NXCD, off = wgid / NXCD; wgid = (xcd < r ? xcd * (q + 1) : r * (q + 1) + (xcd - r) * q) + off; }
;         const int nig = WGM * nN, gid = wgid / nig, fm = gid * WGM, gsz = (nM - fm) < WGM ? (nM - fm) : WGM;
;         u.pm = fm + ((wgid % nig) % gsz); u.pn = (wgid % nig) / gsz; return true;
; template <bool ALIGN = true, class Epi>
; __device__ __forceinline__ void run_gemm(LAS unsigned char* lds, const bf16_t* A, const bf16_t* Bt, int N, int K, const Epi& E) {
;   asm volatile("" : "+s"(N), "+s"(K));
;   pg8::Gemm g{A, Bt, NTOK, N, K};
;   pg8::StaticOrder S; S.init(NTOK, N, (int)gridDim.x, (int)blockIdx.x);
.LBB0_1176:
	v_mov_b64_e32 v[8:9], s[12:13]
	flat_load_dwordx4 v[0:3], v[8:9] offset:192
	flat_load_dwordx4 v[4:7], v[8:9] offset:224
	flat_load_dwordx2 v[150:151], v[8:9] offset:240
	s_waitcnt vmcnt(0)
	flat_load_dwordx2 v[152:153], v[8:9] offset:360
	s_movk_i32 s6, 0x400
	s_ashr_i32 s7, s6, 31
	s_lshr_b32 s7, s7, 24
	s_add_i32 s6, s6, s7
	s_ashr_i32 s10, s6, 8
	s_lshl_b32 s8, s10, 7
	v_mov_b32_e32 v20, v254
	s_cmp_lt_i32 s2, s8
	s_cselect_b64 s[6:7], -1, 0
	s_cmp_ge_i32 s2, s8
	v_readfirstlane_b32 s9, v20
	s_cbranch_scc1 .LBB0_1178
	s_lshl_b32 s14, s10, 3
	s_abs_i32 s15, s14
	v_cvt_f32_u32_e32 v8, s15
	s_lshr_b32 s12, s3, 29
	s_add_i32 s12, s2, s12
	s_ashr_i32 s13, s12, 3
	v_rcp_iflag_f32_e32 v8, v8
	s_and_b32 s12, s12, -8
	s_sub_i32 s12, s2, s12
	s_lshl_b32 s11, s10, 4
	v_mul_f32_e32 v8, 0x4f7ffffe, v8
	v_cvt_u32_f32_e32 v8, v8
	s_lshr_b32 s16, s12, 31
	s_or_b32 s11, s11, s16
	s_sub_i32 s16, 0, s15
	v_readfirstlane_b32 s17, v8
	s_mul_i32 s11, s11, s12
	s_mul_i32 s16, s16, s17
	s_add_i32 s11, s11, s13
	s_mul_hi_u32 s16, s17, s16
	s_abs_i32 s13, s11
	s_add_i32 s17, s17, s16
	s_mul_hi_u32 s16, s13, s17
	s_mul_i32 s17, s16, s15
	s_xor_b32 s12, s11, s14
	s_sub_i32 s13, s13, s17
	s_ashr_i32 s12, s12, 31
	s_add_i32 s17, s16, 1
	s_sub_i32 s18, s13, s15
	s_cmp_ge_u32 s13, s15
	s_cselect_b32 s16, s17, s16
	s_cselect_b32 s13, s18, s13
	s_add_i32 s17, s16, 1
	s_cmp_ge_u32 s13, s15
	s_cselect_b32 s13, s17, s16
	s_xor_b32 s13, s13, s12
	s_sub_i32 s12, s13, s12
	s_lshl_b32 s13, s12, 3
	s_sub_i32 s15, 0x80, s13
	s_min_i32 s15, s15, 8
	s_mul_i32 s12, s12, s14
	s_sub_i32 s11, s11, s12
	s_ashr_i32 s18, s11, 3
	s_mul_i32 s12, s18, s15
	s_sub_i32 s11, s11, s12
	s_add_i32 s30, s11, s13

;     __host__ __device__ bool next(int i, Unit& u) const {
;         const long L = (long)i * G + c; if (L >= nwg) return false;
;         int wgid = (int)L; { const int q = nwg / NXCD, r = nwg % NXCD, xcd = wgid % NXCD, off = wgid / NXCD; wgid = (xcd < r ? xcd * (q + 1) : r * (q + 1) + (xcd - r) * q) + off; }
;         const int nig = WGM * nN, gid = wgid / nig, fm = gid * WGM, gsz = (nM - fm) < WGM ? (nM - fm) : WGM;
;         u.pm = fm + ((wgid % nig) % gsz); u.pn = (wgid % nig) / gsz; return true;
; template <class Epi, class Sched, bool ALIGN_EPI = false, bool SP2 = false>
; __device__ __forceinline__ void gemm_phase(PG8_LAS unsigned char* lds, const Gemm g, const Sched& S, const Epi& E) {
;     ...
;         const bool has_next = S.next(ui + 1, nxt);
;         const char* nA = has_next ? (const char*)g.A + (size_t)nxt.pm * tstep : cA; const char* nB = has_next ? (const char*)g.Bt + (size_t)nxt.pn * tstep : cB;
.LBB0_1184:
	s_add_i32 s59, s59, 1
	s_mul_i32 s8, s59, s43
	s_mul_hi_u32 s9, s59, s42
	s_add_i32 s9, s9, s8
	s_mul_i32 s8, s59, s42
	s_add_u32 s8, s8, s2
	s_addc_u32 s9, s9, s3
	v_cmp_ge_i64_e32 vcc, s[8:9], v[170:171]
	v_cmp_lt_i64_e64 s[10:11], s[8:9], v[170:171]
	s_cbranch_vccnz .LBB0_1186
	s_ashr_i32 s9, s8, 31
	s_lshr_b32 s9, s9, 29
	s_add_i32 s9, s8, s9
	s_ashr_i32 s31, s9, 3
	s_and_b32 s9, s9, -8
	s_sub_i32 s8, s8, s9
	s_lshr_b32 s9, s8, 31
	s_or_b32 s9, s9, s52
	s_mul_i32 s8, s9, s8
	s_add_i32 s8, s8, s31
	s_abs_i32 s31, s8
	s_mul_hi_u32 s60, s31, s55
	s_mul_i32 s61, s60, s51
	s_ashr_i32 s9, s8, 31
	s_sub_i32 s31, s31, s61
	s_xor_b32 s9, s9, s54
	s_add_i32 s61, s60, 1
	s_sub_i32 s62, s31, s51
	s_cmp_ge_u32 s31, s51
	s_cselect_b32 s60, s61, s60
	s_cselect_b32 s31, s62, s31
	s_add_i32 s61, s60, 1
	s_cmp_ge_u32 s31, s51
	s_cselect_b32 s31, s61, s60
	s_xor_b32 s31, s31, s9
	s_sub_i32 s9, s31, s9
	s_lshl_b32 s31, s9, 3
	s_sub_i32 s60, 0x80, s31
	s_min_i32 s61, s60, 8
	s_mul_i32 s9, s9, s50
	s_sub_i32 s8, s8, s9
	s_ashr_i32 s60, s8, 3
	s_mul_i32 s9, s60, s61
	s_sub_i32 s8, s8, s9
	s_add_i32 s61, s8, s31

; #define LAS __attribute__((address_space(3)))
;     __host__ __device__ bool next(int i, Unit& u) const {
;         const long L = (long)i * G + c; if (L >= nwg) return false;
;         int wgid = (int)L; { const int q = nwg / NXCD, r = nwg % NXCD, xcd = wgid % NXCD, off = wgid / NXCD; wgid = (xcd < r ? xcd * (q + 1) : r * (q + 1) + (xcd - r) * q) + off; }
;         const int nig = WGM * nN, gid = wgid / nig, fm = gid * WGM, gsz = (nM - fm) < WGM ? (nM - fm) : WGM;
;         u.pm = fm + ((wgid % nig) % gsz); u.pn = (wgid % nig) / gsz; return true;
; template <bool ALIGN = true, class Epi>
; __device__ __forceinline__ void run_gemm(LAS unsigned char* lds, const bf16_t* A, const bf16_t* Bt, int N, int K, const Epi& E) {
;   asm volatile("" : "+s"(N), "+s"(K));
;   pg8::Gemm g{A, Bt, NTOK, N, K};
;   pg8::StaticOrder S; S.init(NTOK, N, (int)gridDim.x, (int)blockIdx.x);
.LBB0_1324:
	s_or_b64 exec, exec, s[46:47]
	s_mov_b64 s[6:7], s[0:1]
	s_waitcnt lgkmcnt(0)
	s_barrier
	v_mov_b32_e32 v16, v254
	v_mov_b64_e32 v[4:5], s[6:7]
	s_waitcnt vmcnt(0)
	flat_load_dwordx4 v[0:3], v[4:5] offset:192
	flat_load_dwordx2 v[158:159], v[4:5] offset:216
	flat_load_dwordx2 v[160:161], v[4:5] offset:232
	flat_load_dwordx2 v[162:163], v[4:5] offset:336
	s_movk_i32 s7, 0x400
	s_movk_i32 s6, 0xb00
	s_ashr_i32 s8, s7, 31
	s_lshr_b32 s8, s8, 24
	s_add_i32 s7, s7, s8
	s_ashr_i32 s12, s7, 8
	s_lshl_b32 s8, s12, 7
	s_cmp_lt_i32 s2, s8
	s_cselect_b64 s[10:11], -1, 0
	s_cmp_ge_i32 s2, s8
	v_readfirstlane_b32 s9, v16
	s_cbranch_scc1 .LBB0_1326
	s_lshl_b32 s15, s12, 3
	s_abs_i32 s16, s15
	v_cvt_f32_u32_e32 v4, s16
	s_lshr_b32 s13, s3, 29
	s_add_i32 s13, s2, s13
	s_ashr_i32 s14, s13, 3
	v_rcp_iflag_f32_e32 v4, v4
	s_and_b32 s13, s13, -8
	s_sub_i32 s13, s2, s13
	s_lshl_b32 s7, s12, 4
	v_mul_f32_e32 v4, 0x4f7ffffe, v4
	v_cvt_u32_f32_e32 v4, v4
	s_lshr_b32 s17, s13, 31
	s_or_b32 s7, s7, s17
	s_sub_i32 s17, 0, s16
	v_readfirstlane_b32 s18, v4
	s_mul_i32 s7, s7, s13
	s_mul_i32 s17, s17, s18
	s_add_i32 s7, s7, s14
	s_mul_hi_u32 s17, s18, s17
	s_abs_i32 s14, s7
	s_add_i32 s18, s18, s17
	s_mul_hi_u32 s17, s14, s18
	s_mul_i32 s18, s17, s16
	s_xor_b32 s13, s7, s15
	s_sub_i32 s14, s14, s18
	s_ashr_i32 s13, s13, 31
	s_add_i32 s18, s17, 1
	s_sub_i32 s19, s14, s16
	s_cmp_ge_u32 s14, s16
	s_cselect_b32 s17, s18, s17
	s_cselect_b32 s14, s19, s14
	s_add_i32 s18, s17, 1
	s_cmp_ge_u32 s14, s16
	s_cselect_b32 s14, s18, s17
	s_xor_b32 s14, s14, s13
	s_sub_i32 s13, s14, s13
	s_lshl_b32 s14, s13, 3
	s_sub_i32 s16, 0x80, s14
	s_min_i32 s16, s16, 8
	s_mul_i32 s13, s13, s15
	s_sub_i32 s7, s7, s13
	s_ashr_i32 s20, s7, 3
	s_mul_i32 s13, s20, s16
	s_sub_i32 s7, s7, s13
	s_add_i32 s28, s7, s14

;     __host__ __device__ bool next(int i, Unit& u) const {
;         const long L = (long)i * G + c; if (L >= nwg) return false;
;         int wgid = (int)L; { const int q = nwg / NXCD, r = nwg % NXCD, xcd = wgid % NXCD, off = wgid / NXCD; wgid = (xcd < r ? xcd * (q + 1) : r * (q + 1) + (xcd - r) * q) + off; }
;         const int nig = WGM * nN, gid = wgid / nig, fm = gid * WGM, gsz = (nM - fm) < WGM ? (nM - fm) : WGM;
;         u.pm = fm + ((wgid % nig) % gsz); u.pn = (wgid % nig) / gsz; return true;
; template <class Epi, class Sched, bool ALIGN_EPI = false, bool SP2 = false>
; __device__ __forceinline__ void gemm_phase(PG8_LAS unsigned char* lds, const Gemm g, const Sched& S, const Epi& E) {
;     ...
;         const bool has_next = S.next(ui + 1, nxt);
;         const char* nA = has_next ? (const char*)g.A + (size_t)nxt.pm * tstep : cA; const char* nB = has_next ? (const char*)g.Bt + (size_t)nxt.pn * tstep : cB;
.LBB0_1332:
	s_add_i32 s61, s61, 1
	s_mul_i32 s10, s61, s43
	s_mul_hi_u32 s11, s61, s42
	s_add_i32 s11, s11, s10
	s_mul_i32 s10, s61, s42
	s_add_u32 s10, s10, s2
	s_addc_u32 s11, s11, s3
	v_cmp_ge_i64_e32 vcc, s[10:11], v[176:177]
	v_cmp_lt_i64_e64 s[12:13], s[10:11], v[176:177]
	s_cbranch_vccnz .LBB0_1334
	s_ashr_i32 s11, s10, 31
	s_lshr_b32 s11, s11, 29
	s_add_i32 s11, s10, s11
	s_ashr_i32 s29, s11, 3
	s_and_b32 s11, s11, -8
	s_sub_i32 s10, s10, s11
	s_lshr_b32 s11, s10, 31
	s_or_b32 s11, s11, s51
	s_mul_i32 s10, s11, s10
	s_add_i32 s10, s10, s29
	s_abs_i32 s29, s10
	s_mul_hi_u32 s62, s29, s54
	s_mul_i32 s63, s62, s50
	s_ashr_i32 s11, s10, 31
	s_sub_i32 s29, s29, s63
	s_xor_b32 s11, s11, s52
	s_add_i32 s63, s62, 1
	s_sub_i32 s64, s29, s50
	s_cmp_ge_u32 s29, s50
	s_cselect_b32 s62, s63, s62
	s_cselect_b32 s29, s64, s29
	s_add_i32 s63, s62, 1
	s_cmp_ge_u32 s29, s50
	s_cselect_b32 s29, s63, s62
	s_xor_b32 s29, s29, s11
	s_sub_i32 s11, s29, s11
	s_lshl_b32 s29, s11, 3
	s_sub_i32 s62, 0x80, s29
	s_min_i32 s63, s62, 8
	s_mul_i32 s11, s11, s49
	s_sub_i32 s10, s10, s11
	s_ashr_i32 s62, s10, 3
	s_mul_i32 s11, s62, s63
	s_sub_i32 s10, s10, s11
	s_add_i32 s63, s10, s29

;     __host__ __device__ bool next(int i, Unit& u) const {
;         const long L = (long)i * G + c; if (L >= nwg) return false;
;         int wgid = (int)L; { const int q = nwg / NXCD, r = nwg % NXCD, xcd = wgid % NXCD, off = wgid / NXCD; wgid = (xcd < r ? xcd * (q + 1) : r * (q + 1) + (xcd - r) * q) + off; }
;         const int nig = WGM * nN, gid = wgid / nig, fm = gid * WGM, gsz = (nM - fm) < WGM ? (nM - fm) : WGM;
;         u.pm = fm + ((wgid % nig) % gsz); u.pn = (wgid % nig) / gsz; return true;
; template <class Epi, class Sched, bool ALIGN_EPI = false, bool SP2 = false>
; __device__ __forceinline__ void gemm_phase(PG8_LAS unsigned char* lds, const Gemm g, const Sched& S, const Epi& E) {
;     ...
;         const bool has_next = S.next(ui + 1, nxt);
;         const char* nA = has_next ? (const char*)g.A + (size_t)nxt.pm * tstep : cA; const char* nB = has_next ? (const char*)g.Bt + (size_t)nxt.pn * tstep : cB;
.LBB0_1415:
	s_add_i32 s94, s94, 1
	s_mul_i32 s8, s94, s43
	s_mul_hi_u32 s9, s94, s42
	s_add_i32 s9, s9, s8
	s_mul_i32 s8, s94, s42
	s_add_u32 s8, s8, s2
	s_addc_u32 s9, s9, s3
	v_cmp_ge_i64_e32 vcc, s[8:9], v[162:163]
	v_cmp_lt_i64_e64 s[10:11], s[8:9], v[162:163]
	s_cbranch_vccnz .LBB0_1417
	s_ashr_i32 s9, s8, 31
	s_lshr_b32 s9, s9, 29
	s_add_i32 s9, s8, s9
	s_ashr_i32 s13, s9, 3
	s_and_b32 s9, s9, -8
	s_sub_i32 s8, s8, s9
	s_lshr_b32 s9, s8, 31
	s_or_b32 s9, s9, s77
	s_mul_i32 s8, s9, s8
	s_add_i32 s8, s8, s13
	s_abs_i32 s13, s8
	s_mul_hi_u32 s14, s13, s79
	s_mul_i32 s15, s14, s76
	s_ashr_i32 s9, s8, 31
	s_sub_i32 s13, s13, s15
	s_xor_b32 s9, s9, s78
	s_add_i32 s15, s14, 1
	s_sub_i32 s16, s13, s76
	s_cmp_ge_u32 s13, s76
	s_cselect_b32 s14, s15, s14
	s_cselect_b32 s13, s16, s13
	s_add_i32 s15, s14, 1
	s_cmp_ge_u32 s13, s76
	s_cselect_b32 s13, s15, s14
	s_xor_b32 s13, s13, s9
	s_sub_i32 s9, s13, s9
	s_lshl_b32 s13, s9, 3
	s_sub_i32 s14, 0x80, s13
	s_min_i32 s14, s14, 8
	s_mul_i32 s9, s9, s75
	s_sub_i32 s8, s8, s9
	s_ashr_i32 s95, s8, 3
	s_mul_i32 s9, s95, s14
	s_sub_i32 s8, s8, s9
	s_add_i32 s96, s8, s13

; #define LAS __attribute__((address_space(3)))
;     __host__ __device__ bool next(int i, Unit& u) const {
;         const long L = (long)i * G + c; if (L >= nwg) return false;
;         int wgid = (int)L; { const int q = nwg / NXCD, r = nwg % NXCD, xcd = wgid % NXCD, off = wgid / NXCD; wgid = (xcd < r ? xcd * (q + 1) : r * (q + 1) + (xcd - r) * q) + off; }
;         const int nig = WGM * nN, gid = wgid / nig, fm = gid * WGM, gsz = (nM - fm) < WGM ? (nM - fm) : WGM;
;         u.pm = fm + ((wgid % nig) % gsz); u.pn = (wgid % nig) / gsz; return true;
; template <bool ALIGN = true, class Epi>
; __device__ __forceinline__ void run_gemm(LAS unsigned char* lds, const bf16_t* A, const bf16_t* Bt, int N, int K, const Epi& E) {
;   asm volatile("" : "+s"(N), "+s"(K));
;   pg8::Gemm g{A, Bt, NTOK, N, K};
;   pg8::StaticOrder S; S.init(NTOK, N, (int)gridDim.x, (int)blockIdx.x);
.LBB0_1679:
	s_or_b64 exec, exec, s[46:47]
	s_mov_b64 s[6:7], s[0:1]
	s_waitcnt lgkmcnt(0)
	s_barrier
	v_mov_b32_e32 v12, v254
	v_mov_b64_e32 v[0:1], s[6:7]
	flat_load_dwordx2 v[152:153], v[0:1] offset:192
	flat_load_dwordx2 v[154:155], v[0:1] offset:232
	flat_load_dwordx2 v[158:159], v[0:1] offset:520
	flat_load_dwordx2 v[160:161], v[0:1] offset:432
	s_movk_i32 s7, 0x400
	s_movk_i32 s6, 0x400
	s_ashr_i32 s8, s7, 31
	s_lshr_b32 s8, s8, 24
	s_add_i32 s7, s7, s8
	s_ashr_i32 s12, s7, 8
	s_lshl_b32 s8, s12, 7
	s_cmp_lt_i32 s2, s8
	s_cselect_b64 s[10:11], -1, 0
	s_cmp_ge_i32 s2, s8
	v_readfirstlane_b32 s9, v12
	s_cbranch_scc1 .LBB0_1681
	s_lshl_b32 s15, s12, 3
	s_abs_i32 s16, s15
	v_cvt_f32_u32_e32 v0, s16
	s_lshr_b32 s13, s3, 29
	s_add_i32 s13, s2, s13
	s_ashr_i32 s14, s13, 3
	v_rcp_iflag_f32_e32 v0, v0
	s_and_b32 s13, s13, -8
	s_sub_i32 s13, s2, s13
	s_lshl_b32 s7, s12, 4
	v_mul_f32_e32 v0, 0x4f7ffffe, v0
	v_cvt_u32_f32_e32 v0, v0
	s_lshr_b32 s17, s13, 31
	s_or_b32 s7, s7, s17
	s_sub_i32 s17, 0, s16
	v_readfirstlane_b32 s18, v0
	s_mul_i32 s7, s7, s13
	s_mul_i32 s17, s17, s18
	s_add_i32 s7, s7, s14
	s_mul_hi_u32 s17, s18, s17
	s_abs_i32 s14, s7
	s_add_i32 s18, s18, s17
	s_mul_hi_u32 s17, s14, s18
	s_mul_i32 s18, s17, s16
	s_xor_b32 s13, s7, s15
	s_sub_i32 s14, s14, s18
	s_ashr_i32 s13, s13, 31
	s_add_i32 s18, s17, 1
	s_sub_i32 s19, s14, s16
	s_cmp_ge_u32 s14, s16
	s_cselect_b32 s17, s18, s17
	s_cselect_b32 s14, s19, s14
	s_add_i32 s18, s17, 1
	s_cmp_ge_u32 s14, s16
	s_cselect_b32 s14, s18, s17
	s_xor_b32 s14, s14, s13
	s_sub_i32 s13, s14, s13
	s_lshl_b32 s14, s13, 3
	s_sub_i32 s16, 0x80, s14
	s_min_i32 s16, s16, 8
	s_mul_i32 s13, s13, s15
	s_sub_i32 s7, s7, s13
	s_ashr_i32 s20, s7, 3
	s_mul_i32 s13, s20, s16
	s_sub_i32 s7, s7, s13
	s_add_i32 s28, s7, s14

;     __host__ __device__ bool next(int i, Unit& u) const {
;         const long L = (long)i * G + c; if (L >= nwg) return false;
;         int wgid = (int)L; { const int q = nwg / NXCD, r = nwg % NXCD, xcd = wgid % NXCD, off = wgid / NXCD; wgid = (xcd < r ? xcd * (q + 1) : r * (q + 1) + (xcd - r) * q) + off; }
;         const int nig = WGM * nN, gid = wgid / nig, fm = gid * WGM, gsz = (nM - fm) < WGM ? (nM - fm) : WGM;
;         u.pm = fm + ((wgid % nig) % gsz); u.pn = (wgid % nig) / gsz; return true;
; template <class Epi, class Sched, bool ALIGN_EPI = false, bool SP2 = false>
; __device__ __forceinline__ void gemm_phase(PG8_LAS unsigned char* lds, const Gemm g, const Sched& S, const Epi& E) {
;     ...
;         const bool has_next = S.next(ui + 1, nxt);
;         const char* nA = has_next ? (const char*)g.A + (size_t)nxt.pm * tstep : cA; const char* nB = has_next ? (const char*)g.Bt + (size_t)nxt.pn * tstep : cB;
.LBB0_1687:
	s_add_i32 s59, s59, 1
	s_mul_i32 s10, s59, s43
	s_mul_hi_u32 s11, s59, s42
	s_add_i32 s11, s11, s10
	s_mul_i32 s10, s59, s42
	s_add_u32 s10, s10, s2
	s_addc_u32 s11, s11, s3
	v_cmp_ge_i64_e32 vcc, s[10:11], v[174:175]
	v_cmp_lt_i64_e64 s[12:13], s[10:11], v[174:175]
	s_cbranch_vccnz .LBB0_1689
	s_ashr_i32 s11, s10, 31
	s_lshr_b32 s11, s11, 29
	s_add_i32 s11, s10, s11
	s_ashr_i32 s29, s11, 3
	s_and_b32 s11, s11, -8
	s_sub_i32 s10, s10, s11
	s_lshr_b32 s11, s10, 31
	s_or_b32 s11, s11, s51
	s_mul_i32 s10, s11, s10
	s_add_i32 s10, s10, s29
	s_abs_i32 s29, s10
	s_mul_hi_u32 s60, s29, s53
	s_mul_i32 s61, s60, s50
	s_ashr_i32 s11, s10, 31
	s_sub_i32 s29, s29, s61
	s_xor_b32 s11, s11, s52
	s_add_i32 s61, s60, 1
	s_sub_i32 s62, s29, s50
	s_cmp_ge_u32 s29, s50
	s_cselect_b32 s60, s61, s60
	s_cselect_b32 s29, s62, s29
	s_add_i32 s61, s60, 1
	s_cmp_ge_u32 s29, s50
	s_cselect_b32 s29, s61, s60
	s_xor_b32 s29, s29, s11
	s_sub_i32 s11, s29, s11
	s_lshl_b32 s29, s11, 3
	s_sub_i32 s60, 0x80, s29
	s_min_i32 s61, s60, 8
	s_mul_i32 s11, s11, s49
	s_sub_i32 s10, s10, s11
	s_ashr_i32 s60, s10, 3
	s_mul_i32 s11, s60, s61
	s_sub_i32 s10, s10, s11
	s_add_i32 s61, s10, s29

; #define LAS __attribute__((address_space(3)))
;     __host__ __device__ bool next(int i, Unit& u) const {
;         const long L = (long)i * G + c; if (L >= nwg) return false;
;         int wgid = (int)L; { const int q = nwg / NXCD, r = nwg % NXCD, xcd = wgid % NXCD, off = wgid / NXCD; wgid = (xcd < r ? xcd * (q + 1) : r * (q + 1) + (xcd - r) * q) + off; }
;         const int nig = WGM * nN, gid = wgid / nig, fm = gid * WGM, gsz = (nM - fm) < WGM ? (nM - fm) : WGM;
;         u.pm = fm + ((wgid % nig) % gsz); u.pn = (wgid % nig) / gsz; return true;
; template <bool ALIGN = true, class Epi>
; __device__ __forceinline__ void run_gemm(LAS unsigned char* lds, const bf16_t* A, const bf16_t* Bt, int N, int K, const Epi& E) {
;   asm volatile("" : "+s"(N), "+s"(K));
;   pg8::Gemm g{A, Bt, NTOK, N, K};
;   pg8::StaticOrder S; S.init(NTOK, N, (int)gridDim.x, (int)blockIdx.x);
.LBB0_1827:
	s_or_b64 exec, exec, s[46:47]
	s_mov_b64 s[6:7], s[0:1]
	s_waitcnt lgkmcnt(0)
	s_barrier
	v_mov_b32_e32 v12, v254
	s_waitcnt vmcnt(0)
	v_mov_b64_e32 v[0:1], s[6:7]
	flat_load_dwordx2 v[152:153], v[0:1] offset:192
	flat_load_dwordx2 v[154:155], v[0:1] offset:232
	flat_load_dwordx2 v[158:159], v[0:1] offset:352
	flat_load_dwordx2 v[160:161], v[0:1] offset:216
	s_movk_i32 s7, 0x400
	s_movk_i32 s6, 0xb00
	s_ashr_i32 s8, s7, 31
	s_lshr_b32 s8, s8, 24
	s_add_i32 s7, s7, s8
	s_ashr_i32 s12, s7, 8
	s_lshl_b32 s8, s12, 7
	s_cmp_lt_i32 s2, s8
	s_cselect_b64 s[10:11], -1, 0
	s_cmp_ge_i32 s2, s8
	v_readfirstlane_b32 s9, v12
	s_cbranch_scc1 .LBB0_1829
	s_lshl_b32 s15, s12, 3
	s_abs_i32 s16, s15
	v_cvt_f32_u32_e32 v0, s16
	s_lshr_b32 s13, s3, 29
	s_add_i32 s13, s2, s13
	s_ashr_i32 s14, s13, 3
	v_rcp_iflag_f32_e32 v0, v0
	s_and_b32 s13, s13, -8
	s_sub_i32 s13, s2, s13
	s_lshl_b32 s7, s12, 4
	v_mul_f32_e32 v0, 0x4f7ffffe, v0
	v_cvt_u32_f32_e32 v0, v0
	s_lshr_b32 s17, s13, 31
	s_or_b32 s7, s7, s17
	s_sub_i32 s17, 0, s16
	v_readfirstlane_b32 s18, v0
	s_mul_i32 s7, s7, s13
	s_mul_i32 s17, s17, s18
	s_add_i32 s7, s7, s14
	s_mul_hi_u32 s17, s18, s17
	s_abs_i32 s14, s7
	s_add_i32 s18, s18, s17
	s_mul_hi_u32 s17, s14, s18
	s_mul_i32 s18, s17, s16
	s_xor_b32 s13, s7, s15
	s_sub_i32 s14, s14, s18
	s_ashr_i32 s13, s13, 31
	s_add_i32 s18, s17, 1
	s_sub_i32 s19, s14, s16
	s_cmp_ge_u32 s14, s16
	s_cselect_b32 s17, s18, s17
	s_cselect_b32 s14, s19, s14
	s_add_i32 s18, s17, 1
	s_cmp_ge_u32 s14, s16
	s_cselect_b32 s14, s18, s17
	s_xor_b32 s14, s14, s13
	s_sub_i32 s13, s14, s13
	s_lshl_b32 s14, s13, 3
	s_sub_i32 s16, 0x80, s14
	s_min_i32 s16, s16, 8
	s_mul_i32 s13, s13, s15
	s_sub_i32 s7, s7, s13
	s_ashr_i32 s20, s7, 3
	s_mul_i32 s13, s20, s16
	s_sub_i32 s7, s7, s13
	s_add_i32 s28, s7, s14

;     __host__ __device__ bool next(int i, Unit& u) const {
;         const long L = (long)i * G + c; if (L >= nwg) return false;
;         int wgid = (int)L; { const int q = nwg / NXCD, r = nwg % NXCD, xcd = wgid % NXCD, off = wgid / NXCD; wgid = (xcd < r ? xcd * (q + 1) : r * (q + 1) + (xcd - r) * q) + off; }
;         const int nig = WGM * nN, gid = wgid / nig, fm = gid * WGM, gsz = (nM - fm) < WGM ? (nM - fm) : WGM;
;         u.pm = fm + ((wgid % nig) % gsz); u.pn = (wgid % nig) / gsz; return true;
; template <class Epi, class Sched, bool ALIGN_EPI = false, bool SP2 = false>
; __device__ __forceinline__ void gemm_phase(PG8_LAS unsigned char* lds, const Gemm g, const Sched& S, const Epi& E) {
;     ...
;         const bool has_next = S.next(ui + 1, nxt);
;         const char* nA = has_next ? (const char*)g.A + (size_t)nxt.pm * tstep : cA; const char* nB = has_next ? (const char*)g.Bt + (size_t)nxt.pn * tstep : cB;
.LBB0_1916:
	s_add_i32 s63, s63, 1
	s_mul_i32 s8, s63, s43
	s_mul_hi_u32 s9, s63, s42
	s_add_i32 s9, s9, s8
	s_mul_i32 s8, s63, s42
	s_add_u32 s8, s8, s2
	s_addc_u32 s9, s9, s3
	v_cmp_ge_i64_e32 vcc, s[8:9], v[148:149]
	v_cmp_lt_i64_e64 s[10:11], s[8:9], v[148:149]
	s_cbranch_vccnz .LBB0_1918
	s_ashr_i32 s9, s8, 31
	s_lshr_b32 s9, s9, 29
	s_add_i32 s9, s8, s9
	s_ashr_i32 s64, s9, 3
	s_and_b32 s9, s9, -8
	s_sub_i32 s8, s8, s9
	s_cmp_lt_i32 s8, 0
	s_cselect_b32 s9, s30, s23
	s_mul_i32 s8, s9, s8
	s_add_i32 s8, s8, s64
	s_abs_i32 s64, s8
	s_mul_hi_u32 s65, s64, s36
	s_mul_i32 s68, s65, s34
	s_ashr_i32 s9, s8, 31
	s_sub_i32 s64, s64, s68
	s_xor_b32 s9, s9, s35
	s_add_i32 s68, s65, 1
	s_sub_i32 s69, s64, s34
	s_cmp_ge_u32 s64, s34
	s_cselect_b32 s65, s68, s65
	s_cselect_b32 s64, s69, s64
	s_add_i32 s68, s65, 1
	s_cmp_ge_u32 s64, s34
	s_cselect_b32 s64, s68, s65
	s_xor_b32 s64, s64, s9
	s_sub_i32 s9, s64, s9
	s_lshl_b32 s65, s9, 3
	s_sub_i32 s64, 0x80, s65
	s_min_i32 s68, s64, 8
	s_mul_i32 s9, s9, s31
	s_sub_i32 s8, s8, s9
	s_ashr_i32 s64, s8, 3
	s_mul_i32 s9, s64, s68
	s_sub_i32 s8, s8, s9
	s_add_i32 s65, s8, s65

; #define LAS __attribute__((address_space(3)))
;     __host__ __device__ bool next(int i, Unit& u) const {
;         const long L = (long)i * G + c; if (L >= nwg) return false;
;         int wgid = (int)L; { const int q = nwg / NXCD, r = nwg % NXCD, xcd = wgid % NXCD, off = wgid / NXCD; wgid = (xcd < r ? xcd * (q + 1) : r * (q + 1) + (xcd - r) * q) + off; }
;         const int nig = WGM * nN, gid = wgid / nig, fm = gid * WGM, gsz = (nM - fm) < WGM ? (nM - fm) : WGM;
;         u.pm = fm + ((wgid % nig) % gsz); u.pn = (wgid % nig) / gsz; return true;
; template <bool ALIGN = true, class Epi>
; __device__ __forceinline__ void run_gemm(LAS unsigned char* lds, const bf16_t* A, const bf16_t* Bt, int N, int K, const Epi& E) {
;   asm volatile("" : "+s"(N), "+s"(K));
;   pg8::Gemm g{A, Bt, NTOK, N, K};
;   pg8::StaticOrder S; S.init(NTOK, N, (int)gridDim.x, (int)blockIdx.x);
.LBB0_1931:
	v_mov_b64_e32 v[8:9], s[12:13]
	s_waitcnt vmcnt(0) lgkmcnt(0)
	flat_load_dwordx4 v[0:3], v[8:9] offset:192
	flat_load_dwordx4 v[4:7], v[8:9] offset:224
	flat_load_dwordx2 v[150:151], v[8:9] offset:240
	flat_load_dwordx2 v[152:153], v[8:9] offset:368
	s_movk_i32 s6, 0x400
	s_ashr_i32 s7, s6, 31
	s_lshr_b32 s7, s7, 24
	s_add_i32 s6, s6, s7
	s_ashr_i32 s10, s6, 8
	s_lshl_b32 s8, s10, 7
	v_mov_b32_e32 v20, v254
	s_cmp_lt_i32 s2, s8
	s_cselect_b64 s[6:7], -1, 0
	s_cmp_ge_i32 s2, s8
	v_readfirstlane_b32 s9, v20
	s_cbranch_scc1 .LBB0_1933
	s_lshl_b32 s14, s10, 3
	s_abs_i32 s15, s14
	v_cvt_f32_u32_e32 v8, s15
	s_lshr_b32 s12, s3, 29
	s_add_i32 s12, s2, s12
	s_ashr_i32 s13, s12, 3
	v_rcp_iflag_f32_e32 v8, v8
	s_and_b32 s12, s12, -8
	s_sub_i32 s12, s2, s12
	s_lshl_b32 s11, s10, 4
	v_mul_f32_e32 v8, 0x4f7ffffe, v8
	v_cvt_u32_f32_e32 v8, v8
	s_lshr_b32 s16, s12, 31
	s_or_b32 s11, s11, s16
	s_sub_i32 s16, 0, s15
	v_readfirstlane_b32 s17, v8
	s_mul_i32 s11, s11, s12
	s_mul_i32 s16, s16, s17
	s_add_i32 s11, s11, s13
	s_mul_hi_u32 s16, s17, s16
	s_abs_i32 s13, s11
	s_add_i32 s17, s17, s16
	s_mul_hi_u32 s16, s13, s17
	s_mul_i32 s17, s16, s15
	s_xor_b32 s12, s11, s14
	s_sub_i32 s13, s13, s17
	s_ashr_i32 s12, s12, 31
	s_add_i32 s17, s16, 1
	s_sub_i32 s18, s13, s15
	s_cmp_ge_u32 s13, s15
	s_cselect_b32 s16, s17, s16
	s_cselect_b32 s13, s18, s13
	s_add_i32 s17, s16, 1
	s_cmp_ge_u32 s13, s15
	s_cselect_b32 s13, s17, s16
	s_xor_b32 s13, s13, s12
	s_sub_i32 s12, s13, s12
	s_lshl_b32 s13, s12, 3
	s_sub_i32 s15, 0x80, s13
	s_min_i32 s15, s15, 8
	s_mul_i32 s12, s12, s14
	s_sub_i32 s11, s11, s12
	s_ashr_i32 s18, s11, 3
	s_mul_i32 s12, s18, s15
	s_sub_i32 s11, s11, s12
	s_add_i32 s30, s11, s13

;     __host__ __device__ bool next(int i, Unit& u) const {
;         const long L = (long)i * G + c; if (L >= nwg) return false;
;         int wgid = (int)L; { const int q = nwg / NXCD, r = nwg % NXCD, xcd = wgid % NXCD, off = wgid / NXCD; wgid = (xcd < r ? xcd * (q + 1) : r * (q + 1) + (xcd - r) * q) + off; }
;         const int nig = WGM * nN, gid = wgid / nig, fm = gid * WGM, gsz = (nM - fm) < WGM ? (nM - fm) : WGM;
;         u.pm = fm + ((wgid % nig) % gsz); u.pn = (wgid % nig) / gsz; return true;
; template <class Epi, class Sched, bool ALIGN_EPI = false, bool SP2 = false>
; __device__ __forceinline__ void gemm_phase(PG8_LAS unsigned char* lds, const Gemm g, const Sched& S, const Epi& E) {
;     ...
;         const bool has_next = S.next(ui + 1, nxt);
;         const char* nA = has_next ? (const char*)g.A + (size_t)nxt.pm * tstep : cA; const char* nB = has_next ? (const char*)g.Bt + (size_t)nxt.pn * tstep : cB;
.LBB0_1939:
	s_add_i32 s56, s56, 1
	s_mul_i32 s8, s56, s43
	s_mul_hi_u32 s9, s56, s42
	s_add_i32 s9, s9, s8
	s_mul_i32 s8, s56, s42
	s_add_u32 s8, s8, s2
	s_addc_u32 s9, s9, s3
	v_cmp_ge_i64_e32 vcc, s[8:9], v[170:171]
	v_cmp_lt_i64_e64 s[10:11], s[8:9], v[170:171]
	s_cbranch_vccnz .LBB0_1941
	s_ashr_i32 s9, s8, 31
	s_lshr_b32 s9, s9, 29
	s_add_i32 s9, s8, s9
	s_ashr_i32 s31, s9, 3
	s_and_b32 s9, s9, -8
	s_sub_i32 s8, s8, s9
	s_lshr_b32 s9, s8, 31
	s_or_b32 s9, s9, s50
	s_mul_i32 s8, s9, s8
	s_add_i32 s8, s8, s31
	s_abs_i32 s31, s8
	s_mul_hi_u32 s57, s31, s52
	s_mul_i32 s58, s57, s49
	s_ashr_i32 s9, s8, 31
	s_sub_i32 s31, s31, s58
	s_xor_b32 s9, s9, s51
	s_add_i32 s58, s57, 1
	s_sub_i32 s59, s31, s49
	s_cmp_ge_u32 s31, s49
	s_cselect_b32 s57, s58, s57
	s_cselect_b32 s31, s59, s31
	s_add_i32 s58, s57, 1
	s_cmp_ge_u32 s31, s49
	s_cselect_b32 s31, s58, s57
	s_xor_b32 s31, s31, s9
	s_sub_i32 s9, s31, s9
	s_lshl_b32 s31, s9, 3
	s_sub_i32 s57, 0x80, s31
	s_min_i32 s58, s57, 8
	s_mul_i32 s9, s9, s48
	s_sub_i32 s8, s8, s9
	s_ashr_i32 s57, s8, 3
	s_mul_i32 s9, s57, s58
	s_sub_i32 s8, s8, s9
	s_add_i32 s58, s8, s31
